# v154 + P9: leading half's ALIGN drain barrier moved from epilogue entry to after its first output store (epilogue head overlaps trailing half's last MFMA block)
# speedup vs baseline: 1.0059x; 1.0010x over previous
.LBB0_506:
	ds_read_b128 v[146:149], v183
	ds_read_b128 v[150:153], v183 offset:1024
	ds_read_b128 v[154:157], v183 offset:2048
	ds_read_b128 v[158:161], v183 offset:3072
	ds_read_b128 v[162:165], v184
	ds_read_b128 v[166:169], v184 offset:1024
	ds_read_b128 v[186:189], v184 offset:2048
	ds_read_b128 v[190:193], v184 offset:3072
	s_add_u32 s12, s0, 0xfff80080
	s_addc_u32 s13, s1, -1
	s_cmp_eq_u32 s70, 28
	s_cselect_b32 s47, s9, s13
	s_cselect_b32 s46, s41, s12
	s_cselect_b32 s13, s39, s69
	s_cselect_b32 s12, s67, s68
	v_lshl_add_u64 v[170:171], s[0:1], 0, v[138:139]
	s_add_i32 m0, s50, 0xc000
	ds_read_b128 v[194:197], v185
	ds_read_b128 v[198:201], v185 offset:1024
	ds_read_b128 v[202:205], v185 offset:2048
	ds_read_b128 v[206:209], v185 offset:3072
	ds_read_b128 v[214:217], v185 offset:4096
	ds_read_b128 v[218:221], v185 offset:5120
	ds_read_b128 v[222:225], v185 offset:6144
	ds_read_b128 v[226:229], v185 offset:7168
	global_load_lds_dwordx4 v[170:171], off
	v_lshl_add_u64 v[170:171], s[0:1], 0, v[140:141]
	s_add_i32 m0, s50, 0xe000
	s_nop 0
	global_load_lds_dwordx4 v[170:171], off
	s_waitcnt vmcnt(8)
	s_waitcnt lgkmcnt(0)
	s_barrier
	s_setprio 1
	s_waitcnt lgkmcnt(0)
	v_mfma_f32_16x16x32_bf16 v[124:127], v[146:149], v[194:197], v[124:127]
	v_mfma_f32_16x16x32_bf16 v[120:123], v[154:157], v[194:197], v[120:123]
	v_mfma_f32_16x16x32_bf16 v[108:111], v[146:149], v[202:205], v[108:111]
	v_mfma_f32_16x16x32_bf16 v[104:107], v[154:157], v[202:205], v[104:107]
	v_mfma_f32_16x16x32_bf16 v[92:95], v[146:149], v[214:217], v[92:95]
	v_mfma_f32_16x16x32_bf16 v[88:91], v[154:157], v[214:217], v[88:91]
	v_mfma_f32_16x16x32_bf16 v[76:79], v[146:149], v[222:225], v[76:79]
	v_mfma_f32_16x16x32_bf16 v[72:75], v[154:157], v[222:225], v[72:75]
	v_mfma_f32_16x16x32_bf16 v[124:127], v[150:153], v[198:201], v[124:127]
	v_mfma_f32_16x16x32_bf16 v[120:123], v[158:161], v[198:201], v[120:123]
	v_mfma_f32_16x16x32_bf16 v[108:111], v[150:153], v[206:209], v[108:111]
	v_mfma_f32_16x16x32_bf16 v[104:107], v[158:161], v[206:209], v[104:107]
	v_mfma_f32_16x16x32_bf16 v[92:95], v[150:153], v[218:221], v[92:95]
	v_mfma_f32_16x16x32_bf16 v[88:91], v[158:161], v[218:221], v[88:91]
	v_mfma_f32_16x16x32_bf16 v[76:79], v[150:153], v[226:229], v[76:79]
	v_mfma_f32_16x16x32_bf16 v[72:75], v[158:161], v[226:229], v[72:75]
	s_setprio 0
	s_setprio 1
	v_mfma_f32_16x16x32_bf16 v[116:119], v[162:165], v[194:197], v[116:119]
	v_mfma_f32_16x16x32_bf16 v[112:115], v[186:189], v[194:197], v[112:115]
	v_mfma_f32_16x16x32_bf16 v[100:103], v[162:165], v[202:205], v[100:103]
	v_mfma_f32_16x16x32_bf16 v[96:99], v[186:189], v[202:205], v[96:99]
	v_mfma_f32_16x16x32_bf16 v[84:87], v[162:165], v[214:217], v[84:87]
	v_mfma_f32_16x16x32_bf16 v[80:83], v[186:189], v[214:217], v[80:83]
	v_mfma_f32_16x16x32_bf16 v[68:71], v[162:165], v[222:225], v[68:71]
	v_mfma_f32_16x16x32_bf16 v[64:67], v[186:189], v[222:225], v[64:67]
	v_mfma_f32_16x16x32_bf16 v[116:119], v[166:169], v[198:201], v[116:119]
	v_mfma_f32_16x16x32_bf16 v[112:115], v[190:193], v[198:201], v[112:115]
	v_mfma_f32_16x16x32_bf16 v[100:103], v[166:169], v[206:209], v[100:103]
	v_mfma_f32_16x16x32_bf16 v[96:99], v[190:193], v[206:209], v[96:99]
	v_mfma_f32_16x16x32_bf16 v[84:87], v[166:169], v[218:221], v[84:87]
	v_mfma_f32_16x16x32_bf16 v[80:83], v[190:193], v[218:221], v[80:83]
	v_mfma_f32_16x16x32_bf16 v[68:71], v[166:169], v[226:229], v[68:71]
	v_mfma_f32_16x16x32_bf16 v[64:67], v[190:193], v[226:229], v[64:67]
	s_setprio 0
	s_barrier
	s_add_i32 s71, s58, s48
	v_lshl_add_u64 v[170:171], s[12:13], 0, v[132:133]
	s_mov_b32 m0, s71
	ds_read_b128 v[194:197], v185 offset:16384
	ds_read_b128 v[198:201], v185 offset:17408
	ds_read_b128 v[202:205], v185 offset:18432
	ds_read_b128 v[206:209], v185 offset:19456
	ds_read_b128 v[214:217], v185 offset:20480
	ds_read_b128 v[218:221], v185 offset:21504
	ds_read_b128 v[222:225], v185 offset:22528
	ds_read_b128 v[226:229], v185 offset:23552
	global_load_lds_dwordx4 v[170:171], off
	s_add_i32 m0, s71, 0x2000
	s_add_u32 s72, s12, 0x80000
	v_lshl_add_u64 v[210:211], s[12:13], 0, v[128:129]
	s_addc_u32 s73, s13, 0
	s_add_i32 s71, s59, s48
	global_load_lds_dwordx4 v[210:211], off
	v_lshl_add_u64 v[230:231], s[72:73], 0, v[132:133]
	s_mov_b32 m0, s71
	v_lshl_add_u64 v[232:233], s[46:47], 0, v[130:131]
	global_load_lds_dwordx4 v[230:231], off
	v_lshl_add_u64 v[230:231], s[72:73], 0, v[128:129]
	s_add_i32 m0, s71, 0x2000
	s_nop 0
	global_load_lds_dwordx4 v[230:231], off
	v_lshl_add_u64 v[230:231], s[46:47], 0, v[134:135]
	s_mov_b32 m0, s50
	s_nop 0
	global_load_lds_dwordx4 v[230:231], off
	s_mov_b32 m0, s51
	s_nop 0
	global_load_lds_dwordx4 v[232:233], off
	s_waitcnt vmcnt(8)
	s_waitcnt lgkmcnt(0)
	s_barrier
	s_setprio 1
	s_waitcnt lgkmcnt(0)
	v_mfma_f32_16x16x32_bf16 v[60:63], v[146:149], v[194:197], v[60:63]
	v_mfma_f32_16x16x32_bf16 v[56:59], v[154:157], v[194:197], v[56:59]
	v_mfma_f32_16x16x32_bf16 v[44:47], v[146:149], v[202:205], v[44:47]
	v_mfma_f32_16x16x32_bf16 v[40:43], v[154:157], v[202:205], v[40:43]
	v_mfma_f32_16x16x32_bf16 v[28:31], v[146:149], v[214:217], v[28:31]
	v_mfma_f32_16x16x32_bf16 v[24:27], v[154:157], v[214:217], v[24:27]
	v_mfma_f32_16x16x32_bf16 v[12:15], v[146:149], v[222:225], v[12:15]
	v_mfma_f32_16x16x32_bf16 v[8:11], v[154:157], v[222:225], v[8:11]
	v_mfma_f32_16x16x32_bf16 v[60:63], v[150:153], v[198:201], v[60:63]
	v_mfma_f32_16x16x32_bf16 v[56:59], v[158:161], v[198:201], v[56:59]
	v_mfma_f32_16x16x32_bf16 v[44:47], v[150:153], v[206:209], v[44:47]
	v_mfma_f32_16x16x32_bf16 v[40:43], v[158:161], v[206:209], v[40:43]
	v_mfma_f32_16x16x32_bf16 v[28:31], v[150:153], v[218:221], v[28:31]
	v_mfma_f32_16x16x32_bf16 v[24:27], v[158:161], v[218:221], v[24:27]
	v_mfma_f32_16x16x32_bf16 v[12:15], v[150:153], v[226:229], v[12:15]
	v_mfma_f32_16x16x32_bf16 v[8:11], v[158:161], v[226:229], v[8:11]
	s_setprio 0
	s_setprio 1
	v_mfma_f32_16x16x32_bf16 v[52:55], v[162:165], v[194:197], v[52:55]
	v_mfma_f32_16x16x32_bf16 v[48:51], v[186:189], v[194:197], v[48:51]
	v_mfma_f32_16x16x32_bf16 v[36:39], v[162:165], v[202:205], v[36:39]
	v_mfma_f32_16x16x32_bf16 v[32:35], v[186:189], v[202:205], v[32:35]
	v_mfma_f32_16x16x32_bf16 v[20:23], v[162:165], v[214:217], v[20:23]
	v_mfma_f32_16x16x32_bf16 v[16:19], v[186:189], v[214:217], v[16:19]
	v_mfma_f32_16x16x32_bf16 v[4:7], v[162:165], v[222:225], v[4:7]
	v_mfma_f32_16x16x32_bf16 v[0:3], v[186:189], v[222:225], v[0:3]
	v_mfma_f32_16x16x32_bf16 v[52:55], v[166:169], v[198:201], v[52:55]
	v_mfma_f32_16x16x32_bf16 v[48:51], v[190:193], v[198:201], v[48:51]
	v_mfma_f32_16x16x32_bf16 v[36:39], v[166:169], v[206:209], v[36:39]
	v_mfma_f32_16x16x32_bf16 v[32:35], v[190:193], v[206:209], v[32:35]
	v_mfma_f32_16x16x32_bf16 v[20:23], v[166:169], v[218:221], v[20:23]
	v_mfma_f32_16x16x32_bf16 v[16:19], v[190:193], v[218:221], v[16:19]
	v_mfma_f32_16x16x32_bf16 v[4:7], v[166:169], v[226:229], v[4:7]
	v_mfma_f32_16x16x32_bf16 v[0:3], v[190:193], v[226:229], v[0:3]
	s_setprio 0
	s_barrier
	s_add_i32 s71, 0, 0x18000
	s_add_i32 s72, 0, 0x1c000
	v_add_u32_e32 v158, s71, v178
	v_add_u32_e32 v190, s72, v178
	ds_read_b128 v[146:149], v158
	ds_read_b128 v[150:153], v158 offset:1024
	ds_read_b128 v[154:157], v158 offset:2048
	ds_read_b128 v[158:161], v158 offset:3072
	ds_read_b128 v[162:165], v190
	ds_read_b128 v[166:169], v190 offset:1024
	ds_read_b128 v[186:189], v190 offset:2048
	ds_read_b128 v[190:193], v190 offset:3072
	s_add_u32 s46, s46, 0x80000
	s_addc_u32 s47, s47, 0
	s_mov_b32 m0, s52
	v_lshl_add_u64 v[234:235], s[46:47], 0, v[134:135]
	ds_read_b128 v[194:197], v185 offset:32768
	ds_read_b128 v[198:201], v185 offset:33792
	ds_read_b128 v[202:205], v185 offset:34816
	ds_read_b128 v[206:209], v185 offset:35840
	ds_read_b128 v[214:217], v185 offset:36864
	ds_read_b128 v[218:221], v185 offset:37888
	ds_read_b128 v[222:225], v185 offset:38912
	ds_read_b128 v[226:229], v185 offset:39936
	global_load_lds_dwordx4 v[234:235], off
	v_lshl_add_u64 v[234:235], s[46:47], 0, v[130:131]
	s_mov_b32 m0, s53
	s_nop 0
	global_load_lds_dwordx4 v[234:235], off
	s_waitcnt vmcnt(8)
	s_waitcnt lgkmcnt(0)
	s_barrier
	s_setprio 1
	s_waitcnt lgkmcnt(0)
	v_mfma_f32_16x16x32_bf16 v[124:127], v[146:149], v[194:197], v[124:127]
	v_mfma_f32_16x16x32_bf16 v[120:123], v[154:157], v[194:197], v[120:123]
	v_mfma_f32_16x16x32_bf16 v[108:111], v[146:149], v[202:205], v[108:111]
	v_mfma_f32_16x16x32_bf16 v[104:107], v[154:157], v[202:205], v[104:107]
	v_mfma_f32_16x16x32_bf16 v[92:95], v[146:149], v[214:217], v[92:95]
	v_mfma_f32_16x16x32_bf16 v[88:91], v[154:157], v[214:217], v[88:91]
	v_mfma_f32_16x16x32_bf16 v[76:79], v[146:149], v[222:225], v[76:79]
	v_mfma_f32_16x16x32_bf16 v[72:75], v[154:157], v[222:225], v[72:75]
	v_mfma_f32_16x16x32_bf16 v[124:127], v[150:153], v[198:201], v[124:127]
	v_mfma_f32_16x16x32_bf16 v[120:123], v[158:161], v[198:201], v[120:123]
	v_mfma_f32_16x16x32_bf16 v[108:111], v[150:153], v[206:209], v[108:111]
	v_mfma_f32_16x16x32_bf16 v[104:107], v[158:161], v[206:209], v[104:107]
	v_mfma_f32_16x16x32_bf16 v[92:95], v[150:153], v[218:221], v[92:95]
	v_mfma_f32_16x16x32_bf16 v[88:91], v[158:161], v[218:221], v[88:91]
	v_mfma_f32_16x16x32_bf16 v[76:79], v[150:153], v[226:229], v[76:79]
	v_mfma_f32_16x16x32_bf16 v[72:75], v[158:161], v[226:229], v[72:75]
	s_setprio 0
	s_setprio 1
	v_mfma_f32_16x16x32_bf16 v[116:119], v[162:165], v[194:197], v[116:119]
	v_mfma_f32_16x16x32_bf16 v[112:115], v[186:189], v[194:197], v[112:115]
	v_mfma_f32_16x16x32_bf16 v[100:103], v[162:165], v[202:205], v[100:103]
	v_mfma_f32_16x16x32_bf16 v[96:99], v[186:189], v[202:205], v[96:99]
	v_mfma_f32_16x16x32_bf16 v[84:87], v[162:165], v[214:217], v[84:87]
	v_mfma_f32_16x16x32_bf16 v[80:83], v[186:189], v[214:217], v[80:83]
	v_mfma_f32_16x16x32_bf16 v[68:71], v[162:165], v[222:225], v[68:71]
	v_mfma_f32_16x16x32_bf16 v[64:67], v[186:189], v[222:225], v[64:67]
	v_mfma_f32_16x16x32_bf16 v[116:119], v[166:169], v[198:201], v[116:119]
	v_mfma_f32_16x16x32_bf16 v[112:115], v[190:193], v[198:201], v[112:115]
	v_mfma_f32_16x16x32_bf16 v[100:103], v[166:169], v[206:209], v[100:103]
	v_mfma_f32_16x16x32_bf16 v[96:99], v[190:193], v[206:209], v[96:99]
	v_mfma_f32_16x16x32_bf16 v[84:87], v[166:169], v[218:221], v[84:87]
	v_mfma_f32_16x16x32_bf16 v[80:83], v[190:193], v[218:221], v[80:83]
	v_mfma_f32_16x16x32_bf16 v[68:71], v[166:169], v[226:229], v[68:71]
	v_mfma_f32_16x16x32_bf16 v[64:67], v[190:193], v[226:229], v[64:67]
	s_setprio 0
	s_barrier
	s_add_i32 s46, s71, s48
	v_lshl_add_u64 v[170:171], v[170:171], 0, s[22:23]
	s_mov_b32 m0, s46
	ds_read_b128 v[194:197], v185 offset:49152
	ds_read_b128 v[198:201], v185 offset:50176
	ds_read_b128 v[202:205], v185 offset:51200
	ds_read_b128 v[206:209], v185 offset:52224
	ds_read_b128 v[214:217], v185 offset:53248
	ds_read_b128 v[218:221], v185 offset:54272
	ds_read_b128 v[222:225], v185 offset:55296
	ds_read_b128 v[226:229], v185 offset:56320
	global_load_lds_dwordx4 v[170:171], off
	s_add_i32 m0, s46, 0x2000
	s_add_u32 s12, s12, 0x80080
	v_lshl_add_u64 v[170:171], v[210:211], 0, s[22:23]
	s_addc_u32 s13, s13, 0
	s_add_i32 s46, s72, s48
	global_load_lds_dwordx4 v[170:171], off
	v_lshl_add_u64 v[170:171], s[12:13], 0, v[132:133]
	s_mov_b32 m0, s46
	s_nop 0
	global_load_lds_dwordx4 v[170:171], off
	v_lshl_add_u64 v[170:171], s[12:13], 0, v[128:129]
	s_add_i32 m0, s46, 0x2000
	s_nop 0
	global_load_lds_dwordx4 v[170:171], off
	v_lshl_add_u64 v[170:171], v[230:231], 0, s[22:23]
	s_mov_b32 m0, s55
	s_nop 0
	global_load_lds_dwordx4 v[170:171], off
	v_lshl_add_u64 v[170:171], v[232:233], 0, s[22:23]
	s_mov_b32 m0, s56
	s_nop 0
	global_load_lds_dwordx4 v[170:171], off
	s_waitcnt vmcnt(8)
	s_waitcnt lgkmcnt(0)
	s_barrier
	s_setprio 1
	s_waitcnt lgkmcnt(0)
	v_mfma_f32_16x16x32_bf16 v[60:63], v[146:149], v[194:197], v[60:63]
	v_mfma_f32_16x16x32_bf16 v[56:59], v[154:157], v[194:197], v[56:59]
	v_mfma_f32_16x16x32_bf16 v[44:47], v[146:149], v[202:205], v[44:47]
	v_mfma_f32_16x16x32_bf16 v[40:43], v[154:157], v[202:205], v[40:43]
	v_mfma_f32_16x16x32_bf16 v[28:31], v[146:149], v[214:217], v[28:31]
	v_mfma_f32_16x16x32_bf16 v[24:27], v[154:157], v[214:217], v[24:27]
	v_mfma_f32_16x16x32_bf16 v[12:15], v[146:149], v[222:225], v[12:15]
	v_mfma_f32_16x16x32_bf16 v[8:11], v[154:157], v[222:225], v[8:11]
	v_mfma_f32_16x16x32_bf16 v[60:63], v[150:153], v[198:201], v[60:63]
	v_mfma_f32_16x16x32_bf16 v[56:59], v[158:161], v[198:201], v[56:59]
	v_mfma_f32_16x16x32_bf16 v[44:47], v[150:153], v[206:209], v[44:47]
	v_mfma_f32_16x16x32_bf16 v[40:43], v[158:161], v[206:209], v[40:43]
	v_mfma_f32_16x16x32_bf16 v[28:31], v[150:153], v[218:221], v[28:31]
	v_mfma_f32_16x16x32_bf16 v[24:27], v[158:161], v[218:221], v[24:27]
	v_mfma_f32_16x16x32_bf16 v[12:15], v[150:153], v[226:229], v[12:15]
	v_mfma_f32_16x16x32_bf16 v[8:11], v[158:161], v[226:229], v[8:11]
	s_setprio 0
	s_setprio 1
	v_mfma_f32_16x16x32_bf16 v[52:55], v[162:165], v[194:197], v[52:55]
	v_mfma_f32_16x16x32_bf16 v[48:51], v[186:189], v[194:197], v[48:51]
	v_mfma_f32_16x16x32_bf16 v[36:39], v[162:165], v[202:205], v[36:39]
	v_mfma_f32_16x16x32_bf16 v[32:35], v[186:189], v[202:205], v[32:35]
	v_mfma_f32_16x16x32_bf16 v[20:23], v[162:165], v[214:217], v[20:23]
	v_mfma_f32_16x16x32_bf16 v[16:19], v[186:189], v[214:217], v[16:19]
	v_mfma_f32_16x16x32_bf16 v[4:7], v[162:165], v[222:225], v[4:7]
	v_mfma_f32_16x16x32_bf16 v[0:3], v[186:189], v[222:225], v[0:3]
	v_mfma_f32_16x16x32_bf16 v[52:55], v[166:169], v[198:201], v[52:55]
	v_mfma_f32_16x16x32_bf16 v[48:51], v[190:193], v[198:201], v[48:51]
	v_mfma_f32_16x16x32_bf16 v[36:39], v[166:169], v[206:209], v[36:39]
	v_mfma_f32_16x16x32_bf16 v[32:35], v[190:193], v[206:209], v[32:35]
	v_mfma_f32_16x16x32_bf16 v[20:23], v[166:169], v[218:221], v[20:23]
	v_mfma_f32_16x16x32_bf16 v[16:19], v[190:193], v[218:221], v[16:19]
	v_mfma_f32_16x16x32_bf16 v[4:7], v[166:169], v[226:229], v[4:7]
	v_mfma_f32_16x16x32_bf16 v[0:3], v[190:193], v[226:229], v[0:3]
	s_setprio 0
	s_barrier
	s_add_i32 s70, s70, 2
	s_add_u32 s0, s0, 0x100
	s_addc_u32 s1, s1, 0
	s_add_u32 s68, s68, 0x100
	s_addc_u32 s69, s69, 0
	s_cmp_gt_u32 s70, 29
	s_cbranch_scc0 .LBB0_506
	s_and_b64 vcc, exec, s[24:25]
	s_cbranch_vccz .LBB0_509
.LBB0_509:
	v_lshl_add_u32 v162, s8, 8, v177
	v_or_b32_e32 v166, 16, v162
	v_or_b32_e32 v158, 32, v162
	v_or_b32_e32 v156, 48, v162
	v_add_u32_e32 v152, 0x80, v162
	v_add_u32_e32 v150, 0x90, v162
	v_add_u32_e32 v148, 0xa0, v162
	v_add_u32_e32 v146, 0xb0, v162
	s_mov_b64 s[0:1], -1
	s_cmp_lg_u32 s8, s27
	v_ashrrev_i32_e32 v163, 31, v162
	v_ashrrev_i32_e32 v167, 31, v166
	v_ashrrev_i32_e32 v159, 31, v158
	v_ashrrev_i32_e32 v157, 31, v156
	v_ashrrev_i32_e32 v153, 31, v152
	v_ashrrev_i32_e32 v151, 31, v150
	v_ashrrev_i32_e32 v149, 31, v148
	v_ashrrev_i32_e32 v147, 31, v146
	s_cbranch_scc0 .LBB0_511
	v_lshlrev_b64 v[154:155], 7, v[162:163]
	v_lshlrev_b64 v[160:161], 7, v[166:167]
	v_lshl_add_u64 v[154:155], v[136:137], 0, v[154:155]
	v_lshl_add_u64 v[160:161], v[136:137], 0, v[160:161]
	global_load_dwordx4 v[168:171], v[154:155], off
	global_load_dwordx4 v[186:189], v[160:161], off
	global_load_dwordx4 v[190:193], v[154:155], off offset:16
	global_load_dwordx4 v[194:197], v[160:161], off offset:16
	v_lshlrev_b64 v[154:155], 7, v[158:159]
	v_lshlrev_b64 v[160:161], 7, v[156:157]
	v_lshl_add_u64 v[154:155], v[136:137], 0, v[154:155]
	v_lshl_add_u64 v[160:161], v[136:137], 0, v[160:161]
	global_load_dwordx4 v[198:201], v[154:155], off
	global_load_dwordx4 v[202:205], v[160:161], off
	global_load_dwordx4 v[206:209], v[154:155], off offset:16
	global_load_dwordx4 v[214:217], v[160:161], off offset:16
	v_lshlrev_b64 v[154:155], 7, v[152:153]
	v_lshlrev_b64 v[160:161], 7, v[150:151]
	v_lshl_add_u64 v[154:155], v[136:137], 0, v[154:155]
	v_lshl_add_u64 v[160:161], v[136:137], 0, v[160:161]
	global_load_dwordx4 v[218:221], v[154:155], off
	global_load_dwordx4 v[222:225], v[160:161], off
	global_load_dwordx4 v[226:229], v[154:155], off offset:16
	global_load_dwordx4 v[230:233], v[160:161], off offset:16
	v_lshlrev_b64 v[154:155], 7, v[148:149]
	v_lshlrev_b64 v[160:161], 7, v[146:147]
	v_lshl_add_u64 v[154:155], v[136:137], 0, v[154:155]
	v_lshl_add_u64 v[160:161], v[136:137], 0, v[160:161]
	global_load_dwordx4 v[234:237], v[154:155], off offset:16
	global_load_dwordx4 v[238:241], v[154:155], off
	global_load_dwordx4 v[242:245], v[160:161], off offset:16
	global_load_dwordx4 v[246:249], v[160:161], off
	v_mov_b64_e32 v[164:165], s[34:35]
	s_waitcnt vmcnt(0)
	v_mov_b32_e32 v155, v186
	v_mov_b32_e32 v154, v168
	v_mov_b32_e32 v186, v169
	v_mov_b32_e32 v160, v170
	v_mov_b32_e32 v161, v188
	v_mov_b32_e32 v188, v171
	v_mov_b32_e32 v168, v190
	v_mov_b32_e32 v169, v194
	v_mov_b32_e32 v194, v191
	v_mov_b32_e32 v170, v192
	v_mov_b32_e32 v171, v196
	v_mov_b32_e32 v196, v193
	v_mov_b32_e32 v190, v198
	v_mov_b32_e32 v191, v202
	v_mov_b32_e32 v202, v199
	v_mov_b32_e32 v192, v200
	v_mov_b32_e32 v193, v204
	v_mov_b32_e32 v204, v201
	v_mov_b32_e32 v198, v206
	v_mov_b32_e32 v199, v214
	v_mov_b32_e32 v214, v207
	v_mov_b32_e32 v200, v208
	v_mov_b32_e32 v201, v216
	v_mov_b32_e32 v216, v209
	v_pk_add_f32 v[154:155], v[154:155], v[186:187]
	v_pk_add_f32 v[160:161], v[160:161], v[188:189]
	v_pk_add_f32 v[168:169], v[168:169], v[194:195]
	v_pk_add_f32 v[170:171], v[170:171], v[196:197]
	v_pk_add_f32 v[186:187], v[190:191], v[202:203]
	v_pk_add_f32 v[188:189], v[192:193], v[204:205]
	v_pk_add_f32 v[190:191], v[198:199], v[214:215]
	v_pk_add_f32 v[192:193], v[200:201], v[216:217]
	v_pk_add_f32 v[154:155], v[154:155], v[160:161]
	v_pk_add_f32 v[160:161], v[168:169], v[170:171]
	v_pk_add_f32 v[168:169], v[186:187], v[188:189]
	v_pk_add_f32 v[170:171], v[190:191], v[192:193]
	v_pk_add_f32 v[154:155], v[154:155], v[160:161]
	v_pk_add_f32 v[160:161], v[168:169], v[170:171]
	ds_bpermute_b32 v168, v180, v154
	ds_bpermute_b32 v169, v180, v155
	ds_bpermute_b32 v170, v180, v160
	ds_bpermute_b32 v171, v180, v161
	v_mov_b32_e32 v206, v218
	v_mov_b32_e32 v207, v222
	s_waitcnt lgkmcnt(2)
	v_pk_add_f32 v[154:155], v[154:155], v[168:169]
	ds_bpermute_b32 v168, v181, v154
	ds_bpermute_b32 v169, v181, v155
	v_mov_b32_e32 v222, v219
	v_mov_b32_e32 v186, v220
	v_mov_b32_e32 v187, v224
	v_mov_b32_e32 v224, v221
	v_pk_add_f32 v[188:189], v[206:207], v[222:223]
	v_pk_add_f32 v[186:187], v[186:187], v[224:225]
	s_waitcnt lgkmcnt(0)
	v_pk_add_f32 v[154:155], v[154:155], v[168:169]
	v_pk_add_f32 v[160:161], v[160:161], v[170:171]
	v_pk_fma_f32 v[154:155], v[154:155], s[26:27], v[164:165] op_sel_hi:[1,0,0]
	v_pk_add_f32 v[186:187], v[188:189], v[186:187]
	v_mov_b32_e32 v188, v226
	v_mov_b32_e32 v189, v230
	v_mov_b32_e32 v230, v227
	v_mov_b32_e32 v190, v228
	v_mov_b32_e32 v191, v232
	v_mov_b32_e32 v232, v229
	ds_bpermute_b32 v170, v181, v160
	ds_bpermute_b32 v171, v181, v161
	v_mul_f32_e32 v168, 0x4b800000, v154
	v_mul_f32_e32 v169, 0x4b800000, v155
	v_cmp_gt_f32_e32 vcc, s63, v154
	v_cmp_gt_f32_e64 s[0:1], s63, v155
	v_pk_add_f32 v[188:189], v[188:189], v[230:231]
	v_pk_add_f32 v[190:191], v[190:191], v[232:233]
	v_cndmask_b32_e32 v154, v154, v168, vcc
	v_cndmask_b32_e64 v155, v155, v169, s[0:1]
	v_pk_add_f32 v[188:189], v[188:189], v[190:191]
	v_rsq_f32_e32 v154, v154
	v_rsq_f32_e32 v155, v155
	v_pk_add_f32 v[186:187], v[186:187], v[188:189]
	ds_bpermute_b32 v188, v180, v186
	ds_bpermute_b32 v189, v180, v187
	s_waitcnt lgkmcnt(2)
	v_pk_add_f32 v[160:161], v[160:161], v[170:171]
	v_pk_mul_f32 v[168:169], v[154:155], s[36:37] op_sel_hi:[1,0]
	v_pk_fma_f32 v[160:161], v[160:161], s[26:27], v[164:165] op_sel_hi:[1,0,0]
	v_cndmask_b32_e64 v171, v155, v169, s[0:1]
	v_mul_f32_e32 v170, 0x4b800000, v160
	v_cmp_gt_f32_e64 s[8:9], s63, v160
	v_mul_f32_e32 v155, 0x4b800000, v161
	v_cmp_gt_f32_e64 s[0:1], s63, v161
	v_cndmask_b32_e64 v160, v160, v170, s[8:9]
	s_waitcnt lgkmcnt(0)
	v_pk_add_f32 v[186:187], v[186:187], v[188:189]
	v_cndmask_b32_e64 v155, v161, v155, s[0:1]
	v_rsq_f32_e32 v160, v160
	v_rsq_f32_e32 v161, v155
	ds_bpermute_b32 v188, v181, v186
	ds_bpermute_b32 v189, v181, v187
	v_cndmask_b32_e32 v170, v154, v168, vcc
	v_pk_mul_f32 v[154:155], v[160:161], s[36:37] op_sel_hi:[1,0]
	s_nop 0
	v_cndmask_b32_e64 v169, v161, v155, s[0:1]
	v_cndmask_b32_e64 v168, v160, v154, s[8:9]
	s_waitcnt lgkmcnt(0)
	v_pk_add_f32 v[154:155], v[186:187], v[188:189]
	v_mov_b32_e32 v160, v238
	v_mov_b32_e32 v161, v246
	v_mov_b32_e32 v246, v239
	v_mov_b32_e32 v186, v240
	v_mov_b32_e32 v187, v248
	v_mov_b32_e32 v248, v241
	v_pk_add_f32 v[160:161], v[160:161], v[246:247]
	v_pk_add_f32 v[186:187], v[186:187], v[248:249]
	v_mov_b32_e32 v188, v236
	v_pk_add_f32 v[160:161], v[160:161], v[186:187]
	v_mov_b32_e32 v186, v234
	v_mov_b32_e32 v187, v242
	v_mov_b32_e32 v242, v235
	v_mov_b32_e32 v189, v244
	v_mov_b32_e32 v244, v237
	v_pk_add_f32 v[186:187], v[186:187], v[242:243]
	v_pk_add_f32 v[188:189], v[188:189], v[244:245]
	v_pk_fma_f32 v[154:155], v[154:155], s[26:27], v[164:165] op_sel_hi:[1,0,0]
	v_pk_add_f32 v[186:187], v[186:187], v[188:189]
	v_mul_f32_e32 v188, 0x4b800000, v154
	v_pk_add_f32 v[160:161], v[160:161], v[186:187]
	ds_bpermute_b32 v186, v180, v160
	ds_bpermute_b32 v187, v180, v161
	v_cmp_gt_f32_e32 vcc, s63, v154
	v_cmp_gt_f32_e64 s[0:1], s63, v155
	s_waitcnt lgkmcnt(0)
	v_pk_add_f32 v[160:161], v[160:161], v[186:187]
	ds_bpermute_b32 v186, v181, v160
	ds_bpermute_b32 v187, v181, v161
	v_cndmask_b32_e32 v154, v154, v188, vcc
	v_mul_f32_e32 v188, 0x4b800000, v155
	v_cndmask_b32_e64 v155, v155, v188, s[0:1]
	v_rsq_f32_e32 v154, v154
	s_waitcnt lgkmcnt(0)
	v_pk_add_f32 v[160:161], v[160:161], v[186:187]
	v_rsq_f32_e32 v155, v155
	v_pk_fma_f32 v[160:161], v[160:161], s[26:27], v[164:165] op_sel_hi:[1,0,0]
	s_nop 0
	v_mul_f32_e32 v164, 0x4b800000, v160
	v_cmp_gt_f32_e64 s[8:9], s63, v160
	v_cmp_gt_f32_e64 s[12:13], s63, v161
	s_nop 0
	v_cndmask_b32_e64 v160, v160, v164, s[8:9]
	v_rsq_f32_e32 v164, v160
	v_mul_f32_e32 v160, 0x4b800000, v161
	v_cndmask_b32_e64 v160, v161, v160, s[12:13]
	v_rsq_f32_e32 v165, v160
	v_pk_mul_f32 v[160:161], v[154:155], s[36:37] op_sel_hi:[1,0]
	s_nop 0
	v_cndmask_b32_e64 v161, v155, v161, s[0:1]
	v_cndmask_b32_e32 v160, v154, v160, vcc
	v_pk_mul_f32 v[154:155], v[164:165], s[36:37] op_sel_hi:[1,0]
	s_mov_b64 s[0:1], 0
	v_cndmask_b32_e64 v155, v165, v155, s[12:13]
	v_cndmask_b32_e64 v154, v164, v154, s[8:9]

.LBB0_513:
	v_mov_b64_e32 v[164:165], s[16:17]
	v_mad_u64_u32 v[188:189], s[0:1], v162, s64, v[164:165]
	v_lshl_or_b32 v186, s65, 7, v182
	v_mov_b32_e32 v162, v189
	v_ashrrev_i32_e32 v187, 31, v186
	v_mad_u64_u32 v[162:163], s[0:1], v163, s64, v[162:163]
	s_waitcnt lgkmcnt(0)
	v_pk_mul_f32 v[124:125], v[124:125], v[170:171] op_sel_hi:[1,0]
	v_mov_b32_e32 v189, v162
	v_lshlrev_b64 v[162:163], 1, v[186:187]
	v_mul_f32_e32 v186, 0xbfb8aa3b, v124
	v_exp_f32_e32 v190, v186
	v_mul_f32_e32 v186, 0xbfb8aa3b, v125
	v_exp_f32_e32 v191, v186
	v_pk_mul_f32 v[126:127], v[126:127], v[170:171] op_sel_hi:[1,0]
	v_lshl_add_u64 v[186:187], v[188:189], 0, v[162:163]
	v_add_f32_e32 v188, 1.0, v190
	v_add_f32_e32 v189, 1.0, v191
	v_mul_f32_e32 v190, 0xbfb8aa3b, v126
	v_mul_f32_e32 v191, 0xbfb8aa3b, v127
	v_rcp_f32_e32 v188, v188
	v_rcp_f32_e32 v189, v189
	v_exp_f32_e32 v190, v190
	v_exp_f32_e32 v191, v191
	v_pk_mul_f32 v[116:117], v[116:117], v[170:171] op_sel_hi:[1,0]
	v_pk_mul_f32 v[124:125], v[124:125], v[188:189]
	v_add_f32_e32 v188, 1.0, v190
	v_add_f32_e32 v189, 1.0, v191
	v_rcp_f32_e32 v188, v188
	v_rcp_f32_e32 v189, v189
	v_pk_mul_f32 v[116:117], v[116:117], v[124:125]
	v_pk_mul_f32 v[120:121], v[120:121], v[170:171] op_sel_hi:[1,0]
	v_cvt_pk_bf16_f32 v116, v116, v117
	v_pk_mul_f32 v[124:125], v[126:127], v[188:189]
	v_pk_mul_f32 v[118:119], v[118:119], v[170:171] op_sel_hi:[1,0]
	v_mul_f32_e32 v117, 0xbfb8aa3b, v120
	v_pk_mul_f32 v[118:119], v[118:119], v[124:125]
	v_exp_f32_e32 v124, v117
	v_mul_f32_e32 v117, 0xbfb8aa3b, v121
	v_exp_f32_e32 v125, v117
	v_pk_mul_f32 v[122:123], v[122:123], v[170:171] op_sel_hi:[1,0]
	v_cvt_pk_bf16_f32 v117, v118, v119
	v_add_f32_e32 v118, 1.0, v124
	v_add_f32_e32 v119, 1.0, v125
	v_mul_f32_e32 v124, 0xbfb8aa3b, v122
	v_mul_f32_e32 v125, 0xbfb8aa3b, v123
	v_rcp_f32_e32 v118, v118
	v_rcp_f32_e32 v119, v119
	v_exp_f32_e32 v124, v124
	v_exp_f32_e32 v125, v125
	v_pk_mul_f32 v[112:113], v[112:113], v[170:171] op_sel_hi:[1,0]
	v_pk_mul_f32 v[118:119], v[120:121], v[118:119]
	v_add_f32_e32 v120, 1.0, v124
	v_add_f32_e32 v121, 1.0, v125
	v_rcp_f32_e32 v120, v120
	v_rcp_f32_e32 v121, v121
	v_pk_mul_f32 v[112:113], v[112:113], v[118:119]
	v_pk_mul_f32 v[114:115], v[114:115], v[170:171] op_sel_hi:[1,0]
	v_cvt_pk_bf16_f32 v118, v112, v113
	v_pk_mul_f32 v[112:113], v[122:123], v[120:121]
	v_pk_mul_f32 v[108:109], v[108:109], v[170:171] op_sel:[0,1]
	v_pk_mul_f32 v[112:113], v[114:115], v[112:113]
	v_pk_mul_f32 v[110:111], v[110:111], v[170:171] op_sel:[0,1]
	v_cvt_pk_bf16_f32 v119, v112, v113
	v_mad_u64_u32 v[112:113], s[0:1], v166, s64, v[164:165]
	v_mov_b32_e32 v114, v113
	v_mad_u64_u32 v[114:115], s[0:1], v167, s64, v[114:115]
	v_mov_b32_e32 v113, v114
	v_mul_f32_e32 v114, 0xbfb8aa3b, v108
	v_mul_f32_e32 v115, 0xbfb8aa3b, v109
	v_exp_f32_e32 v114, v114
	v_exp_f32_e32 v115, v115
	global_store_dwordx4 v[186:187], v[116:119], off
	s_cmp_lg_u64 s[24:25], 0
	s_cbranch_scc0 .Lp9_latebar
	s_barrier
.Lp9_latebar:
	v_pk_mul_f32 v[100:101], v[100:101], v[170:171] op_sel:[0,1]
	v_add_f32_e32 v114, 1.0, v114
	v_add_f32_e32 v115, 1.0, v115
	v_mul_f32_e32 v116, 0xbfb8aa3b, v110
	v_mul_f32_e32 v117, 0xbfb8aa3b, v111
	v_rcp_f32_e32 v114, v114
	v_rcp_f32_e32 v115, v115
	v_exp_f32_e32 v116, v116
	v_exp_f32_e32 v117, v117
	v_pk_mul_f32 v[104:105], v[104:105], v[170:171] op_sel:[0,1]
	v_pk_mul_f32 v[108:109], v[108:109], v[114:115]
	v_add_f32_e32 v114, 1.0, v116
	v_add_f32_e32 v115, 1.0, v117
	v_rcp_f32_e32 v114, v114
	v_rcp_f32_e32 v115, v115
	v_pk_mul_f32 v[100:101], v[100:101], v[108:109]
	v_pk_mul_f32 v[102:103], v[102:103], v[170:171] op_sel:[0,1]
	v_cvt_pk_bf16_f32 v100, v100, v101
	v_pk_mul_f32 v[108:109], v[110:111], v[114:115]
	v_mul_f32_e32 v101, 0xbfb8aa3b, v104
	v_pk_mul_f32 v[102:103], v[102:103], v[108:109]
	v_exp_f32_e32 v108, v101
	v_mul_f32_e32 v101, 0xbfb8aa3b, v105
	v_exp_f32_e32 v109, v101
	v_pk_mul_f32 v[106:107], v[106:107], v[170:171] op_sel:[0,1]
	v_cvt_pk_bf16_f32 v101, v102, v103
	v_add_f32_e32 v102, 1.0, v108
	v_add_f32_e32 v103, 1.0, v109
	v_mul_f32_e32 v108, 0xbfb8aa3b, v106
	v_mul_f32_e32 v109, 0xbfb8aa3b, v107
	v_rcp_f32_e32 v102, v102
	v_rcp_f32_e32 v103, v103
	v_exp_f32_e32 v108, v108
	v_exp_f32_e32 v109, v109
	v_pk_mul_f32 v[96:97], v[96:97], v[170:171] op_sel:[0,1]
	v_pk_mul_f32 v[102:103], v[104:105], v[102:103]
	v_add_f32_e32 v104, 1.0, v108
	v_add_f32_e32 v105, 1.0, v109
	v_rcp_f32_e32 v104, v104
	v_rcp_f32_e32 v105, v105
	v_pk_mul_f32 v[96:97], v[96:97], v[102:103]
	v_pk_mul_f32 v[98:99], v[98:99], v[170:171] op_sel:[0,1]
	v_cvt_pk_bf16_f32 v102, v96, v97
	v_pk_mul_f32 v[96:97], v[106:107], v[104:105]
	v_pk_mul_f32 v[92:93], v[92:93], v[168:169] op_sel_hi:[1,0]
	v_pk_mul_f32 v[96:97], v[98:99], v[96:97]
	v_lshl_add_u64 v[112:113], v[112:113], 0, v[162:163]
	v_cvt_pk_bf16_f32 v103, v96, v97
	v_mad_u64_u32 v[96:97], s[0:1], v158, s64, v[164:165]
	v_mov_b32_e32 v98, v97
	v_mad_u64_u32 v[98:99], s[0:1], v159, s64, v[98:99]
	v_mov_b32_e32 v97, v98
	v_mul_f32_e32 v98, 0xbfb8aa3b, v92
	v_mul_f32_e32 v99, 0xbfb8aa3b, v93
	v_exp_f32_e32 v98, v98
	v_exp_f32_e32 v99, v99
	v_pk_mul_f32 v[94:95], v[94:95], v[168:169] op_sel_hi:[1,0]
	global_store_dwordx4 v[112:113], v[100:103], off
	v_add_f32_e32 v98, 1.0, v98
	v_add_f32_e32 v99, 1.0, v99
	v_mul_f32_e32 v100, 0xbfb8aa3b, v94
	v_mul_f32_e32 v101, 0xbfb8aa3b, v95
	v_rcp_f32_e32 v98, v98
	v_rcp_f32_e32 v99, v99
	v_exp_f32_e32 v100, v100
	v_exp_f32_e32 v101, v101
	v_pk_mul_f32 v[84:85], v[84:85], v[168:169] op_sel_hi:[1,0]
	v_pk_mul_f32 v[92:93], v[92:93], v[98:99]
	v_add_f32_e32 v98, 1.0, v100
	v_add_f32_e32 v99, 1.0, v101
	v_rcp_f32_e32 v98, v98
	v_rcp_f32_e32 v99, v99
	v_pk_mul_f32 v[84:85], v[84:85], v[92:93]
	v_pk_mul_f32 v[88:89], v[88:89], v[168:169] op_sel_hi:[1,0]
	v_cvt_pk_bf16_f32 v84, v84, v85
	v_pk_mul_f32 v[92:93], v[94:95], v[98:99]
	v_pk_mul_f32 v[86:87], v[86:87], v[168:169] op_sel_hi:[1,0]
	v_mul_f32_e32 v85, 0xbfb8aa3b, v88
	v_pk_mul_f32 v[86:87], v[86:87], v[92:93]
	v_exp_f32_e32 v92, v85
	v_mul_f32_e32 v85, 0xbfb8aa3b, v89
	v_exp_f32_e32 v93, v85
	v_pk_mul_f32 v[90:91], v[90:91], v[168:169] op_sel_hi:[1,0]
	v_cvt_pk_bf16_f32 v85, v86, v87
	v_add_f32_e32 v86, 1.0, v92
	v_add_f32_e32 v87, 1.0, v93
	v_mul_f32_e32 v92, 0xbfb8aa3b, v90
	v_mul_f32_e32 v93, 0xbfb8aa3b, v91
	v_rcp_f32_e32 v86, v86
	v_rcp_f32_e32 v87, v87
	v_exp_f32_e32 v92, v92
	v_exp_f32_e32 v93, v93
	v_pk_mul_f32 v[80:81], v[80:81], v[168:169] op_sel_hi:[1,0]
	v_pk_mul_f32 v[86:87], v[88:89], v[86:87]
	v_add_f32_e32 v88, 1.0, v92
	v_add_f32_e32 v89, 1.0, v93
	v_rcp_f32_e32 v88, v88
	v_rcp_f32_e32 v89, v89
	v_pk_mul_f32 v[80:81], v[80:81], v[86:87]
	v_pk_mul_f32 v[82:83], v[82:83], v[168:169] op_sel_hi:[1,0]
	v_cvt_pk_bf16_f32 v86, v80, v81
	v_pk_mul_f32 v[80:81], v[90:91], v[88:89]
	v_pk_mul_f32 v[76:77], v[76:77], v[168:169] op_sel:[0,1]
	v_pk_mul_f32 v[80:81], v[82:83], v[80:81]
	v_lshl_add_u64 v[96:97], v[96:97], 0, v[162:163]
	v_cvt_pk_bf16_f32 v87, v80, v81
	v_mad_u64_u32 v[80:81], s[0:1], v156, s64, v[164:165]
	v_mov_b32_e32 v82, v81
	v_mad_u64_u32 v[82:83], s[0:1], v157, s64, v[82:83]
	v_mov_b32_e32 v81, v82
	v_mul_f32_e32 v82, 0xbfb8aa3b, v76
	v_mul_f32_e32 v83, 0xbfb8aa3b, v77
	v_exp_f32_e32 v82, v82
	v_exp_f32_e32 v83, v83
	v_pk_mul_f32 v[78:79], v[78:79], v[168:169] op_sel:[0,1]
	global_store_dwordx4 v[96:97], v[84:87], off
	v_add_f32_e32 v82, 1.0, v82
	v_add_f32_e32 v83, 1.0, v83
	v_mul_f32_e32 v84, 0xbfb8aa3b, v78
	v_mul_f32_e32 v85, 0xbfb8aa3b, v79
	v_rcp_f32_e32 v82, v82
	v_rcp_f32_e32 v83, v83
	v_exp_f32_e32 v84, v84
	v_exp_f32_e32 v85, v85
	v_pk_mul_f32 v[68:69], v[68:69], v[168:169] op_sel:[0,1]
	v_pk_mul_f32 v[76:77], v[76:77], v[82:83]
	v_add_f32_e32 v82, 1.0, v84
	v_add_f32_e32 v83, 1.0, v85
	v_rcp_f32_e32 v82, v82
	v_rcp_f32_e32 v83, v83
	v_pk_mul_f32 v[68:69], v[68:69], v[76:77]
	v_pk_mul_f32 v[72:73], v[72:73], v[168:169] op_sel:[0,1]
	v_cvt_pk_bf16_f32 v68, v68, v69
	v_pk_mul_f32 v[76:77], v[78:79], v[82:83]
	v_pk_mul_f32 v[70:71], v[70:71], v[168:169] op_sel:[0,1]
	v_mul_f32_e32 v69, 0xbfb8aa3b, v72
	v_pk_mul_f32 v[70:71], v[70:71], v[76:77]
	v_exp_f32_e32 v76, v69
	v_mul_f32_e32 v69, 0xbfb8aa3b, v73
	v_exp_f32_e32 v77, v69
	v_pk_mul_f32 v[74:75], v[74:75], v[168:169] op_sel:[0,1]
	v_cvt_pk_bf16_f32 v69, v70, v71
	v_add_f32_e32 v70, 1.0, v76
	v_add_f32_e32 v71, 1.0, v77
	v_mul_f32_e32 v76, 0xbfb8aa3b, v74
	v_mul_f32_e32 v77, 0xbfb8aa3b, v75
	v_rcp_f32_e32 v70, v70
	v_rcp_f32_e32 v71, v71
	v_exp_f32_e32 v76, v76
	v_exp_f32_e32 v77, v77
	v_pk_mul_f32 v[64:65], v[64:65], v[168:169] op_sel:[0,1]
	v_pk_mul_f32 v[70:71], v[72:73], v[70:71]
	v_add_f32_e32 v72, 1.0, v76
	v_add_f32_e32 v73, 1.0, v77
	v_rcp_f32_e32 v72, v72
	v_rcp_f32_e32 v73, v73
	v_pk_mul_f32 v[64:65], v[64:65], v[70:71]
	v_pk_mul_f32 v[66:67], v[66:67], v[168:169] op_sel:[0,1]
	v_cvt_pk_bf16_f32 v70, v64, v65
	v_pk_mul_f32 v[64:65], v[74:75], v[72:73]
	v_pk_mul_f32 v[60:61], v[60:61], v[160:161] op_sel_hi:[1,0]
	v_pk_mul_f32 v[64:65], v[66:67], v[64:65]
	v_lshl_add_u64 v[80:81], v[80:81], 0, v[162:163]
	v_cvt_pk_bf16_f32 v71, v64, v65
	v_mad_u64_u32 v[64:65], s[0:1], v152, s64, v[164:165]
	v_mov_b32_e32 v66, v65
	v_mad_u64_u32 v[66:67], s[0:1], v153, s64, v[66:67]
	v_mov_b32_e32 v65, v66
	v_mul_f32_e32 v66, 0xbfb8aa3b, v60
	v_mul_f32_e32 v67, 0xbfb8aa3b, v61
	v_exp_f32_e32 v66, v66
	v_exp_f32_e32 v67, v67
	v_pk_mul_f32 v[62:63], v[62:63], v[160:161] op_sel_hi:[1,0]
	global_store_dwordx4 v[80:81], v[68:71], off
	v_add_f32_e32 v66, 1.0, v66
	v_add_f32_e32 v67, 1.0, v67
	v_mul_f32_e32 v68, 0xbfb8aa3b, v62
	v_mul_f32_e32 v69, 0xbfb8aa3b, v63
	v_rcp_f32_e32 v66, v66
	v_rcp_f32_e32 v67, v67
	v_exp_f32_e32 v68, v68
	v_exp_f32_e32 v69, v69
	v_pk_mul_f32 v[52:53], v[52:53], v[160:161] op_sel_hi:[1,0]
	v_pk_mul_f32 v[60:61], v[60:61], v[66:67]
	v_add_f32_e32 v66, 1.0, v68
	v_add_f32_e32 v67, 1.0, v69
	v_rcp_f32_e32 v66, v66
	v_rcp_f32_e32 v67, v67
	v_pk_mul_f32 v[52:53], v[52:53], v[60:61]
	v_pk_mul_f32 v[56:57], v[56:57], v[160:161] op_sel_hi:[1,0]
	v_cvt_pk_bf16_f32 v52, v52, v53
	v_pk_mul_f32 v[60:61], v[62:63], v[66:67]
	v_pk_mul_f32 v[54:55], v[54:55], v[160:161] op_sel_hi:[1,0]
	v_mul_f32_e32 v53, 0xbfb8aa3b, v56
	v_pk_mul_f32 v[54:55], v[54:55], v[60:61]
	v_exp_f32_e32 v60, v53
	v_mul_f32_e32 v53, 0xbfb8aa3b, v57
	v_exp_f32_e32 v61, v53
	v_pk_mul_f32 v[58:59], v[58:59], v[160:161] op_sel_hi:[1,0]
	v_cvt_pk_bf16_f32 v53, v54, v55
	v_add_f32_e32 v54, 1.0, v60
	v_add_f32_e32 v55, 1.0, v61
	v_mul_f32_e32 v60, 0xbfb8aa3b, v58
	v_mul_f32_e32 v61, 0xbfb8aa3b, v59
	v_rcp_f32_e32 v54, v54
	v_rcp_f32_e32 v55, v55
	v_exp_f32_e32 v60, v60
	v_exp_f32_e32 v61, v61
	v_pk_mul_f32 v[48:49], v[48:49], v[160:161] op_sel_hi:[1,0]
	v_pk_mul_f32 v[54:55], v[56:57], v[54:55]
	v_add_f32_e32 v56, 1.0, v60
	v_add_f32_e32 v57, 1.0, v61
	v_rcp_f32_e32 v56, v56
	v_rcp_f32_e32 v57, v57
	v_pk_mul_f32 v[48:49], v[48:49], v[54:55]
	v_pk_mul_f32 v[50:51], v[50:51], v[160:161] op_sel_hi:[1,0]
	v_cvt_pk_bf16_f32 v54, v48, v49
	v_pk_mul_f32 v[48:49], v[58:59], v[56:57]
	v_pk_mul_f32 v[44:45], v[44:45], v[160:161] op_sel:[0,1]
	v_pk_mul_f32 v[48:49], v[50:51], v[48:49]
	v_lshl_add_u64 v[64:65], v[64:65], 0, v[162:163]
	v_cvt_pk_bf16_f32 v55, v48, v49
	v_mad_u64_u32 v[48:49], s[0:1], v150, s64, v[164:165]
	v_mov_b32_e32 v50, v49
	v_mad_u64_u32 v[50:51], s[0:1], v151, s64, v[50:51]
	v_mov_b32_e32 v49, v50
	v_mul_f32_e32 v50, 0xbfb8aa3b, v44
	v_mul_f32_e32 v51, 0xbfb8aa3b, v45
	v_exp_f32_e32 v50, v50
	v_exp_f32_e32 v51, v51
	v_pk_mul_f32 v[46:47], v[46:47], v[160:161] op_sel:[0,1]
	global_store_dwordx4 v[64:65], v[52:55], off
	v_add_f32_e32 v50, 1.0, v50
	v_add_f32_e32 v51, 1.0, v51
	v_mul_f32_e32 v52, 0xbfb8aa3b, v46
	v_mul_f32_e32 v53, 0xbfb8aa3b, v47
	v_rcp_f32_e32 v50, v50
	v_rcp_f32_e32 v51, v51
	v_exp_f32_e32 v52, v52
	v_exp_f32_e32 v53, v53
	v_pk_mul_f32 v[36:37], v[36:37], v[160:161] op_sel:[0,1]
	v_pk_mul_f32 v[44:45], v[44:45], v[50:51]
	v_add_f32_e32 v50, 1.0, v52
	v_add_f32_e32 v51, 1.0, v53
	v_rcp_f32_e32 v50, v50
	v_rcp_f32_e32 v51, v51
	v_pk_mul_f32 v[36:37], v[36:37], v[44:45]
	v_pk_mul_f32 v[40:41], v[40:41], v[160:161] op_sel:[0,1]
	v_cvt_pk_bf16_f32 v36, v36, v37
	v_pk_mul_f32 v[44:45], v[46:47], v[50:51]
	v_pk_mul_f32 v[38:39], v[38:39], v[160:161] op_sel:[0,1]
	v_mul_f32_e32 v37, 0xbfb8aa3b, v40
	v_pk_mul_f32 v[38:39], v[38:39], v[44:45]
	v_exp_f32_e32 v44, v37
	v_mul_f32_e32 v37, 0xbfb8aa3b, v41
	v_exp_f32_e32 v45, v37
	v_pk_mul_f32 v[42:43], v[42:43], v[160:161] op_sel:[0,1]
	v_cvt_pk_bf16_f32 v37, v38, v39
	v_add_f32_e32 v38, 1.0, v44
	v_add_f32_e32 v39, 1.0, v45
	v_mul_f32_e32 v44, 0xbfb8aa3b, v42
	v_mul_f32_e32 v45, 0xbfb8aa3b, v43
	v_rcp_f32_e32 v38, v38
	v_rcp_f32_e32 v39, v39
	v_exp_f32_e32 v44, v44
	v_exp_f32_e32 v45, v45
	v_pk_mul_f32 v[32:33], v[32:33], v[160:161] op_sel:[0,1]
	v_pk_mul_f32 v[38:39], v[40:41], v[38:39]
	v_add_f32_e32 v40, 1.0, v44
	v_add_f32_e32 v41, 1.0, v45
	v_rcp_f32_e32 v40, v40
	v_rcp_f32_e32 v41, v41
	v_pk_mul_f32 v[32:33], v[32:33], v[38:39]
	v_pk_mul_f32 v[34:35], v[34:35], v[160:161] op_sel:[0,1]
	v_cvt_pk_bf16_f32 v38, v32, v33
	v_pk_mul_f32 v[32:33], v[42:43], v[40:41]
	v_pk_mul_f32 v[28:29], v[28:29], v[154:155] op_sel_hi:[1,0]
	v_pk_mul_f32 v[32:33], v[34:35], v[32:33]
	v_lshl_add_u64 v[48:49], v[48:49], 0, v[162:163]
	v_cvt_pk_bf16_f32 v39, v32, v33
	v_mad_u64_u32 v[32:33], s[0:1], v148, s64, v[164:165]
	v_mov_b32_e32 v34, v33
	v_mad_u64_u32 v[34:35], s[0:1], v149, s64, v[34:35]
	v_mov_b32_e32 v33, v34
	v_mul_f32_e32 v34, 0xbfb8aa3b, v28
	v_mul_f32_e32 v35, 0xbfb8aa3b, v29
	v_exp_f32_e32 v34, v34
	v_exp_f32_e32 v35, v35
	v_pk_mul_f32 v[30:31], v[30:31], v[154:155] op_sel_hi:[1,0]
	global_store_dwordx4 v[48:49], v[36:39], off
	v_add_f32_e32 v34, 1.0, v34
	v_add_f32_e32 v35, 1.0, v35
	v_mul_f32_e32 v36, 0xbfb8aa3b, v30
	v_mul_f32_e32 v37, 0xbfb8aa3b, v31
	v_rcp_f32_e32 v34, v34
	v_rcp_f32_e32 v35, v35
	v_exp_f32_e32 v36, v36
	v_exp_f32_e32 v37, v37
	v_pk_mul_f32 v[20:21], v[20:21], v[154:155] op_sel_hi:[1,0]
	v_pk_mul_f32 v[28:29], v[28:29], v[34:35]
	v_add_f32_e32 v34, 1.0, v36
	v_add_f32_e32 v35, 1.0, v37
	v_rcp_f32_e32 v34, v34
	v_rcp_f32_e32 v35, v35
	v_pk_mul_f32 v[20:21], v[20:21], v[28:29]
	v_pk_mul_f32 v[24:25], v[24:25], v[154:155] op_sel_hi:[1,0]
	v_cvt_pk_bf16_f32 v20, v20, v21
	v_pk_mul_f32 v[28:29], v[30:31], v[34:35]
	v_pk_mul_f32 v[22:23], v[22:23], v[154:155] op_sel_hi:[1,0]
	v_mul_f32_e32 v21, 0xbfb8aa3b, v24
	v_pk_mul_f32 v[22:23], v[22:23], v[28:29]
	v_exp_f32_e32 v28, v21
	v_mul_f32_e32 v21, 0xbfb8aa3b, v25
	v_exp_f32_e32 v29, v21
	v_pk_mul_f32 v[26:27], v[26:27], v[154:155] op_sel_hi:[1,0]
	v_cvt_pk_bf16_f32 v21, v22, v23
	v_add_f32_e32 v22, 1.0, v28
	v_add_f32_e32 v23, 1.0, v29
	v_mul_f32_e32 v28, 0xbfb8aa3b, v26
	v_mul_f32_e32 v29, 0xbfb8aa3b, v27
	v_rcp_f32_e32 v22, v22
	v_rcp_f32_e32 v23, v23
	v_exp_f32_e32 v28, v28
	v_exp_f32_e32 v29, v29
	v_pk_mul_f32 v[16:17], v[16:17], v[154:155] op_sel_hi:[1,0]
	v_pk_mul_f32 v[22:23], v[24:25], v[22:23]
	v_add_f32_e32 v24, 1.0, v28
	v_add_f32_e32 v25, 1.0, v29
	v_rcp_f32_e32 v24, v24
	v_rcp_f32_e32 v25, v25
	v_pk_mul_f32 v[16:17], v[16:17], v[22:23]
	v_pk_mul_f32 v[18:19], v[18:19], v[154:155] op_sel_hi:[1,0]
	v_cvt_pk_bf16_f32 v22, v16, v17
	v_pk_mul_f32 v[16:17], v[26:27], v[24:25]
	v_pk_mul_f32 v[12:13], v[12:13], v[154:155] op_sel:[0,1]
	v_pk_mul_f32 v[16:17], v[18:19], v[16:17]
	v_lshl_add_u64 v[32:33], v[32:33], 0, v[162:163]
	v_cvt_pk_bf16_f32 v23, v16, v17
	v_mad_u64_u32 v[16:17], s[0:1], v146, s64, v[164:165]
	v_mov_b32_e32 v18, v17
	v_mad_u64_u32 v[18:19], s[0:1], v147, s64, v[18:19]
	v_mov_b32_e32 v17, v18
	v_mul_f32_e32 v18, 0xbfb8aa3b, v12
	v_mul_f32_e32 v19, 0xbfb8aa3b, v13
	v_exp_f32_e32 v18, v18
	v_exp_f32_e32 v19, v19
	v_pk_mul_f32 v[14:15], v[14:15], v[154:155] op_sel:[0,1]
	global_store_dwordx4 v[32:33], v[20:23], off
	v_add_f32_e32 v18, 1.0, v18
	v_add_f32_e32 v19, 1.0, v19
	v_mul_f32_e32 v20, 0xbfb8aa3b, v14
	v_mul_f32_e32 v21, 0xbfb8aa3b, v15
	v_rcp_f32_e32 v18, v18
	v_rcp_f32_e32 v19, v19
	v_exp_f32_e32 v20, v20
	v_exp_f32_e32 v21, v21
	v_pk_mul_f32 v[4:5], v[4:5], v[154:155] op_sel:[0,1]
	v_pk_mul_f32 v[12:13], v[12:13], v[18:19]
	v_add_f32_e32 v18, 1.0, v20
	v_add_f32_e32 v19, 1.0, v21
	v_rcp_f32_e32 v18, v18
	v_rcp_f32_e32 v19, v19
	v_pk_mul_f32 v[4:5], v[4:5], v[12:13]
	v_pk_mul_f32 v[8:9], v[8:9], v[154:155] op_sel:[0,1]
	v_cvt_pk_bf16_f32 v4, v4, v5
	v_pk_mul_f32 v[12:13], v[14:15], v[18:19]
	v_pk_mul_f32 v[6:7], v[6:7], v[154:155] op_sel:[0,1]
	v_mul_f32_e32 v5, 0xbfb8aa3b, v8
	v_pk_mul_f32 v[6:7], v[6:7], v[12:13]
	v_exp_f32_e32 v12, v5
	v_mul_f32_e32 v5, 0xbfb8aa3b, v9
	v_exp_f32_e32 v13, v5
	v_pk_mul_f32 v[10:11], v[10:11], v[154:155] op_sel:[0,1]
	v_cvt_pk_bf16_f32 v5, v6, v7
	v_add_f32_e32 v6, 1.0, v12
	v_add_f32_e32 v7, 1.0, v13
	v_mul_f32_e32 v12, 0xbfb8aa3b, v10
	v_mul_f32_e32 v13, 0xbfb8aa3b, v11
	v_rcp_f32_e32 v6, v6
	v_rcp_f32_e32 v7, v7
	v_exp_f32_e32 v12, v12
	v_exp_f32_e32 v13, v13
	v_pk_mul_f32 v[0:1], v[0:1], v[154:155] op_sel:[0,1]
	v_pk_mul_f32 v[6:7], v[8:9], v[6:7]
	v_add_f32_e32 v8, 1.0, v12
	v_add_f32_e32 v9, 1.0, v13
	v_rcp_f32_e32 v8, v8
	v_rcp_f32_e32 v9, v9
	v_pk_mul_f32 v[0:1], v[0:1], v[6:7]
	v_pk_mul_f32 v[2:3], v[2:3], v[154:155] op_sel:[0,1]
	v_cvt_pk_bf16_f32 v6, v0, v1
	v_pk_mul_f32 v[0:1], v[10:11], v[8:9]
	v_lshl_add_u64 v[16:17], v[16:17], 0, v[162:163]
	v_pk_mul_f32 v[0:1], v[2:3], v[0:1]
	s_andn2_b64 vcc, exec, s[6:7]
	v_cvt_pk_bf16_f32 v7, v0, v1
	s_mov_b64 s[0:1], -1
	global_store_dwordx4 v[16:17], v[4:7], off
	s_cbranch_vccnz .LBB0_502
	s_andn2_b64 vcc, exec, s[18:19]
	s_cbranch_vccnz .LBB0_501
	s_barrier
	s_branch .LBB0_501
